# grid barrier: the FIRST local arriver of each XCD also issues an early buffer_wbl2 (un-waited) so the last arriver's mandatory write-back finds L2 mostly clean
# baseline (speedup 1.0000x reference)
; __device__ __forceinline__ unsigned xb_ld(unsigned* p)              { return __hip_atomic_load(p, __ATOMIC_RELAXED, __HIP_MEMORY_SCOPE_AGENT); }
; __device__ __forceinline__ unsigned xb_add(unsigned* p, unsigned v) { return __hip_atomic_fetch_add(p, v, __ATOMIC_RELAXED, __HIP_MEMORY_SCOPE_AGENT); }
; #define XB_SPIN(cond, bar) do { unsigned _sp = 0; while (cond) { __builtin_amdgcn_s_sleep(1); \
;     if ((++_sp & 255u) == 0u) { if (xb_ld(&(bar)[XB_TMO])) break; if (_sp > XB_SPIN_CAP) { atomicAdd(&(bar)[XB_TMO], 1u); break; } } } } while (0)
; __device__ __forceinline__ void xcd_barrier(const XcdBarrier& b) {
;     ...
;         unsigned nloc = b.st[0], nx = b.st[1];
;         if (nloc == 0u) { xcd_barrier_complete(bar, b.x, nloc, nx); b.st[0] = nloc; b.st[1] = nx; }
;         const unsigned old = xb_add(&bar[XB_XSUB(b.x)], 1u);
;         const unsigned gen = old / nloc;
;         if (old + 1u == (gen + 1u) * nloc) {
;             __builtin_amdgcn_fence(__ATOMIC_RELEASE, "agent");
;             asm volatile("s_waitcnt vmcnt(0)" ::: "memory");
;             const unsigned og = xb_add(&bar[XB_TOP], 1u);
;             const unsigned tg = og / nx;
;             if (og + 1u == (tg + 1u) * nx) xb_add(&bar[XB_TOPGEN], 1u);
;             else XB_SPIN(xb_ld(&bar[XB_TOPGEN]) == tg, bar);
.Lxb0_poll:
	s_waitcnt lgkmcnt(0)
	v_cmp_ne_u32_e32 vcc, v5, v4
	s_cbranch_vccnz .Lxb0_nf
	buffer_wbl2 sc1
.Lxb0_nf:
	v_add_u32_e32 v1, 1, v1
	v_mul_lo_u32 v1, v1, v0
	v_mov_b32_e32 v2, 0x303000
	s_mov_b32 s3, 0
